# row-tile scans: remainder by group size 8 as mask; hand-written SwiGLU epilogue (r^2 folded into reciprocal, running row pointer)
# speedup vs baseline: 1.0095x; 1.0015x over previous
; template <bool WANT_PN> __device__ __forceinline__ int unit_tile(int M, int N, int G, int c, int i) {
;     const int nM = M / 256, nN = N / 256, nwg = nM * nN; const long L = (long)i * G + c; if (L >= nwg) return -1;
;     int wgid = (int)L; { const int q = nwg / pg8::NXCD, r = nwg % pg8::NXCD, xcd = wgid % pg8::NXCD, off = wgid / pg8::NXCD; wgid = (xcd < r ? xcd * (q + 1) : r * (q + 1) + (xcd - r) * q) + off; }
;     const int nig = pg8::WGM * nN, gid = wgid / nig, fm = gid * pg8::WGM, gsz = (nM - fm) < pg8::WGM ? (nM - fm) : pg8::WGM;
;     return WANT_PN ? (wgid % nig) / gsz : fm + ((wgid % nig) % gsz);
.LBB0_200:
	v_cmp_gt_i64_e32 vcc, s[0:1], v[0:1]
	s_mov_b32 s5, -1
	s_cbranch_vccnz .LBB0_202
	s_ashr_i32 s5, s0, 31
	s_lshr_b32 s5, s5, 29
	s_add_i32 s5, s0, s5
	s_ashr_i32 s8, s5, 3
	s_and_b32 s5, s5, -8
	s_sub_i32 s5, s0, s5
	s_lshr_b32 s9, s5, 31
	s_or_b32 s9, s9, 0x160
	s_mul_i32 s5, s9, s5
	s_add_i32 s5, s5, s8
	s_mul_hi_i32 s8, s5, 0x2e8ba2e9
	s_lshr_b32 s9, s8, 31
	s_ashr_i32 s8, s8, 5
	s_add_i32 s8, s8, s9
	s_lshl_b32 s9, s8, 3
	s_mulk_i32 s8, 0xb0
	s_sub_i32 s5, s5, s8
	s_and_b32 s5, s5, 7
	s_add_i32 s5, s5, s9

; template <bool WANT_PN> __device__ __forceinline__ int unit_tile(int M, int N, int G, int c, int i) {
;     const int nM = M / 256, nN = N / 256, nwg = nM * nN; const long L = (long)i * G + c; if (L >= nwg) return -1;
;     int wgid = (int)L; { const int q = nwg / pg8::NXCD, r = nwg % pg8::NXCD, xcd = wgid % pg8::NXCD, off = wgid / pg8::NXCD; wgid = (xcd < r ? xcd * (q + 1) : r * (q + 1) + (xcd - r) * q) + off; }
;     const int nig = pg8::WGM * nN, gid = wgid / nig, fm = gid * pg8::WGM, gsz = (nM - fm) < pg8::WGM ? (nM - fm) : pg8::WGM;
;     return WANT_PN ? (wgid % nig) / gsz : fm + ((wgid % nig) % gsz);
.LBB0_390:
	v_cmp_gt_i64_e32 vcc, s[0:1], v[0:1]
	s_mov_b32 s5, -1
	s_cbranch_vccnz .LBB0_392
	s_ashr_i32 s5, s0, 31
	s_lshr_b32 s5, s5, 29
	s_add_i32 s5, s0, s5
	s_ashr_i32 s8, s5, 3
	s_and_b32 s5, s5, -8
	s_sub_i32 s5, s0, s5
	s_lshr_b32 s9, s5, 31
	s_or_b32 s9, s9, 0x60
	s_mul_i32 s5, s9, s5
	s_add_i32 s5, s5, s8
	s_mul_hi_i32 s8, s5, 0x2aaaaaab
	s_lshr_b32 s9, s8, 31
	s_ashr_i32 s8, s8, 3
	s_add_i32 s8, s8, s9
	s_lshl_b32 s9, s8, 3
	s_mul_i32 s8, s8, 48
	s_sub_i32 s5, s5, s8
	s_and_b32 s5, s5, 7
	s_add_i32 s5, s5, s9

; template <bool WANT_PN> __device__ __forceinline__ int unit_tile(int M, int N, int G, int c, int i) {
;     const int nM = M / 256, nN = N / 256, nwg = nM * nN; const long L = (long)i * G + c; if (L >= nwg) return -1;
;     int wgid = (int)L; { const int q = nwg / pg8::NXCD, r = nwg % pg8::NXCD, xcd = wgid % pg8::NXCD, off = wgid / pg8::NXCD; wgid = (xcd < r ? xcd * (q + 1) : r * (q + 1) + (xcd - r) * q) + off; }
;     const int nig = pg8::WGM * nN, gid = wgid / nig, fm = gid * pg8::WGM, gsz = (nM - fm) < pg8::WGM ? (nM - fm) : pg8::WGM;
;     return WANT_PN ? (wgid % nig) / gsz : fm + ((wgid % nig) % gsz);
.LBB0_1166:
	v_cmp_gt_i64_e32 vcc, s[0:1], v[0:1]
	s_mov_b32 s5, -1
	s_cbranch_vccnz .LBB0_1168
	s_ashr_i32 s5, s0, 31
	s_lshr_b32 s5, s5, 29
	s_add_i32 s5, s0, s5
	s_ashr_i32 s6, s5, 3
	s_and_b32 s5, s5, -8
	s_sub_i32 s5, s0, s5
	s_lshr_b32 s7, s5, 31
	s_bitset1_b32 s7, 7
	s_mul_i32 s5, s7, s5
	s_add_i32 s5, s5, s6
	s_ashr_i32 s6, s5, 31
	s_lshr_b32 s6, s6, 26
	s_add_i32 s6, s5, s6
	s_ashr_i32 s7, s6, 6
	s_lshl_b32 s7, s7, 3
	s_andn2_b32 s6, s6, 63
	s_sub_i32 s5, s5, s6
	s_and_b32 s5, s5, 7
	s_add_i32 s5, s5, s7
